# k34 + LDS-staged full-line sample-row tiles also in P5 and the P8 gate GEMM (K=1024)
# speedup vs baseline: 1.0316x; 1.0081x over previous
; #define LAS __attribute__((address_space(3)))
; template <class Elem>
; __device__ __forceinline__ void gemm_small64(LAS unsigned char* lds, const bf16* A, const bf16* Bt, int K, int r0, int c0, const Elem& E) {
;     int tid_ = threadIdx.x; asm volatile("" : "+v"(tid_));
;     const int tid = tid_, lane = tid & 63, w = __builtin_amdgcn_readfirstlane(tid >> 6), fr = lane & 15, fq = lane >> 4;
;     const int kw = K >> 3, k0 = w * kw;
;     f32x4 acc[4][4];
; #pragma unroll
;     for (int i = 0; i < 4; ++i)
; #pragma unroll
;         for (int j = 0; j < 4; ++j) acc[i][j] = (f32x4){0.f, 0.f, 0.f, 0.f};
;     const bf16* ap = A + (size_t)(r0 + fr) * K + k0 + 8 * fq;
;     const bf16* bp = Bt + (size_t)(c0 + fr) * K + k0 + 8 * fq;
;     const size_t s16 = (size_t)16 * K;
; #pragma unroll 4
;     for (int ks = 0; ks < kw; ks += 32) {
;         bf16x8 a[4], b[4];
; #pragma unroll
;         for (int i = 0; i < 4; ++i) { a[i] = *(const bf16x8*)(ap + i * s16 + ks); b[i] = *(const bf16x8*)(bp + i * s16 + ks); }
; #pragma unroll
;         for (int rb = 0; rb < 4; ++rb)
; #pragma unroll
;             for (int cb = 0; cb < 4; ++cb) acc[rb][cb] = __builtin_amdgcn_mfma_f32_16x16x32_bf16(b[cb], a[rb], acc[rb][cb], 0, 0, 0);
;     }
.LBB0_945:
	s_and_b32 s6, s5, 0xffffffc0
	v_mov_b32_e32 v7, v192
	s_addk_i32 s6, 0x4000
	s_and_b32 s0, s3, 0x3c0
	v_readfirstlane_b32 s7, v7
	v_and_b32_e32 v126, 15, v7
	s_lshl_b32 s18, s7, 1
	v_or_b32_e32 v2, s6, v126
	s_and_b32 s18, s18, 0xffffff80
	v_ashrrev_i32_e32 v3, 31, v2
	v_lshlrev_b64 v[2:3], 11, v[2:3]
	s_ashr_i32 s19, s18, 31
	s_lshl_b64 s[18:19], s[18:19], 1
	v_lshl_add_u64 v[2:3], s[56:57], 0, v[2:3]
	v_and_b32_e32 v0, 48, v7
	v_lshl_add_u64 v[2:3], v[2:3], 0, s[18:19]
	v_or_b32_e32 v8, s0, v126
	v_lshl_add_u64 v[2:3], v[2:3], 0, v[0:1]
	v_lshlrev_b32_e32 v8, 11, v8
	v_mov_b32_e32 v9, v1
	v_add_co_u32_e32 v116, vcc, s9, v2
	v_lshl_add_u64 v[8:9], s[12:13], 0, v[8:9]
	s_nop 0
	v_addc_co_u32_e32 v117, vcc, 0, v3, vcc
	v_lshl_add_u64 v[8:9], v[8:9], 0, s[18:19]
	v_add_co_u32_e32 v120, vcc, s14, v2
	v_lshl_add_u64 v[108:109], v[8:9], 0, v[0:1]
	s_lshr_b32 s101, s7, 6
	v_mov_b32_e32 v29, v126
	v_lshrrev_b32_e32 v10, 3, v246
	v_and_b32_e32 v11, 7, v246
	v_lshrrev_b32_e32 v12, 1, v10
	v_xor_b32_e32 v13, v11, v12
	v_xor_b32_e32 v14, 4, v13
	v_mul_u32_u24_e32 v15, 0x800, v10
	v_lshl_add_u32 v16, v13, 4, v15
	v_lshl_add_u32 v17, v14, 4, v15
	v_mov_b32_e32 v19, 0x800
	v_mad_u32_u24 v18, v29, v19, v0
	v_sub_co_u32_e32 v20, vcc, v2, v18
	s_nop 1
	v_subbrev_co_u32_e32 v21, vcc, 0, v3, vcc
	v_sub_co_u32_e32 v22, vcc, v108, v18
	s_nop 1
	v_subbrev_co_u32_e32 v23, vcc, 0, v109, vcc
	v_mov_b32_e32 v128, v16
	v_add_u32_e32 v129, 0x4000, v17
	v_add_u32_e32 v130, 0x8000, v16
	v_add_u32_e32 v131, 0xc000, v17
	v_add_u32_e32 v132, 0x10000, v16
	v_add_u32_e32 v133, 0x14000, v17
	v_add_u32_e32 v134, 0x18000, v16
	v_add_u32_e32 v135, 0x1c000, v17
	v_readfirstlane_b32 s98, v20
	v_readfirstlane_b32 s99, v21
	v_readfirstlane_b32 s18, v22
	v_readfirstlane_b32 s19, v23
	s_nop 4
	s_mul_i32 s100, s101, 0x4400
	v_lshrrev_b32_e32 v25, 1, v29
	v_lshrrev_b32_e32 v26, 4, v0
	v_xor_b32_e32 v26, v26, v25
	v_lshlrev_b32_e32 v27, 7, v29
	v_lshl_add_u32 v27, v26, 4, v27
	v_add_u32_e32 v27, s100, v27
	v_xor_b32_e32 v28, 64, v27
	s_add_i32 m0, s100, 0x0
	s_nop 0
	global_load_lds_dwordx4 v128, s[98:99]
	s_add_i32 m0, s100, 0x400
	s_nop 0
	global_load_lds_dwordx4 v129, s[98:99]
	s_add_i32 m0, s100, 0x800
	s_nop 0
	global_load_lds_dwordx4 v130, s[98:99]
	s_add_i32 m0, s100, 0xc00
	s_nop 0
	global_load_lds_dwordx4 v131, s[98:99]
	s_add_i32 m0, s100, 0x1000
	s_nop 0
	global_load_lds_dwordx4 v132, s[98:99]
	s_add_i32 m0, s100, 0x1400
	s_nop 0
	global_load_lds_dwordx4 v133, s[98:99]
	s_add_i32 m0, s100, 0x1800
	s_nop 0
	global_load_lds_dwordx4 v134, s[98:99]
	s_add_i32 m0, s100, 0x1c00
	s_nop 0
	global_load_lds_dwordx4 v135, s[98:99]
	s_add_i32 m0, s100, 0x2000
	s_nop 0
	global_load_lds_dwordx4 v128, s[18:19]
	s_add_i32 m0, s100, 0x2400
	s_nop 0
	global_load_lds_dwordx4 v129, s[18:19]
	s_add_i32 m0, s100, 0x2800
	s_nop 0
	global_load_lds_dwordx4 v130, s[18:19]
	s_add_i32 m0, s100, 0x2c00
	s_nop 0
	global_load_lds_dwordx4 v131, s[18:19]
	s_add_i32 m0, s100, 0x3000
	s_nop 0
	global_load_lds_dwordx4 v132, s[18:19]
	s_add_i32 m0, s100, 0x3400
	s_nop 0
	global_load_lds_dwordx4 v133, s[18:19]
	s_add_i32 m0, s100, 0x3800
	s_nop 0
	global_load_lds_dwordx4 v134, s[18:19]
	s_add_i32 m0, s100, 0x3c00
	s_nop 0
	global_load_lds_dwordx4 v135, s[18:19]
	s_add_u32 s98, s98, 0x80
	s_addc_u32 s99, s99, 0
	s_add_u32 s18, s18, 0x80
	s_addc_u32 s19, s19, 0
	s_waitcnt vmcnt(0)
	ds_read_b128 v[160:163], v27
	ds_read_b128 v[164:167], v27 offset:2048
	ds_read_b128 v[168:171], v27 offset:4096
	ds_read_b128 v[172:175], v27 offset:6144
	ds_read_b128 v[196:199], v27 offset:8192
	ds_read_b128 v[200:203], v27 offset:10240
	ds_read_b128 v[204:207], v27 offset:12288
	ds_read_b128 v[208:211], v27 offset:14336
	ds_read_b128 v[176:179], v28
	ds_read_b128 v[180:183], v28 offset:2048
	ds_read_b128 v[184:187], v28 offset:4096
	ds_read_b128 v[188:191], v28 offset:6144
	ds_read_b128 v[212:215], v28 offset:8192
	ds_read_b128 v[216:219], v28 offset:10240
	ds_read_b128 v[220:223], v28 offset:12288
	ds_read_b128 v[224:227], v28 offset:14336
	s_waitcnt lgkmcnt(0)
	s_add_i32 m0, s100, 0x0
	s_nop 0
	global_load_lds_dwordx4 v128, s[98:99]
	s_add_i32 m0, s100, 0x400
	s_nop 0
	global_load_lds_dwordx4 v129, s[98:99]
	s_add_i32 m0, s100, 0x800
	s_nop 0
	global_load_lds_dwordx4 v130, s[98:99]
	s_add_i32 m0, s100, 0xc00
	s_nop 0
	global_load_lds_dwordx4 v131, s[98:99]
	s_add_i32 m0, s100, 0x1000
	s_nop 0
	global_load_lds_dwordx4 v132, s[98:99]
	s_add_i32 m0, s100, 0x1400
	s_nop 0
	global_load_lds_dwordx4 v133, s[98:99]
	s_add_i32 m0, s100, 0x1800
	s_nop 0
	global_load_lds_dwordx4 v134, s[98:99]
	s_add_i32 m0, s100, 0x1c00
	s_nop 0
	global_load_lds_dwordx4 v135, s[98:99]
	s_add_i32 m0, s100, 0x2000
	s_nop 0
	global_load_lds_dwordx4 v128, s[18:19]
	s_add_i32 m0, s100, 0x2400
	s_nop 0
	global_load_lds_dwordx4 v129, s[18:19]
	s_add_i32 m0, s100, 0x2800
	s_nop 0
	global_load_lds_dwordx4 v130, s[18:19]
	s_add_i32 m0, s100, 0x2c00
	s_nop 0
	global_load_lds_dwordx4 v131, s[18:19]
	s_add_i32 m0, s100, 0x3000
	s_nop 0
	global_load_lds_dwordx4 v132, s[18:19]
	s_add_i32 m0, s100, 0x3400
	s_nop 0
	global_load_lds_dwordx4 v133, s[18:19]
	s_add_i32 m0, s100, 0x3800
	s_nop 0
	global_load_lds_dwordx4 v134, s[18:19]
	s_add_i32 m0, s100, 0x3c00
	s_nop 0
	global_load_lds_dwordx4 v135, s[18:19]
	s_add_u32 s98, s98, 0x80
	s_addc_u32 s99, s99, 0
	s_add_u32 s18, s18, 0x80
	s_addc_u32 s19, s19, 0
	v_mfma_f32_16x16x32_bf16 v[64:67], v[196:199], v[160:163], 0
	v_mfma_f32_16x16x32_bf16 v[68:71], v[200:203], v[160:163], 0
	v_mfma_f32_16x16x32_bf16 v[72:75], v[204:207], v[160:163], 0
	v_mfma_f32_16x16x32_bf16 v[76:79], v[208:211], v[160:163], 0
; #define LAS __attribute__((address_space(3)))
; template <class Elem>
; __device__ __forceinline__ void gemm_small64(LAS unsigned char* lds, const bf16* A, const bf16* Bt, int K, int r0, int c0, const Elem& E) {
;     ...
;     for (int ks = 0; ks < kw; ks += 32) {
;         bf16x8 a[4], b[4];
; #pragma unroll
;         for (int i = 0; i < 4; ++i) { a[i] = *(const bf16x8*)(ap + i * s16 + ks); b[i] = *(const bf16x8*)(bp + i * s16 + ks); }
; #pragma unroll
;         for (int rb = 0; rb < 4; ++rb)
; #pragma unroll
;             for (int cb = 0; cb < 4; ++cb) acc[rb][cb] = __builtin_amdgcn_mfma_f32_16x16x32_bf16(b[cb], a[rb], acc[rb][cb], 0, 0, 0);
;     }
;     LAS float* P = (LAS float*)lds;
; #pragma unroll
;     for (int rb = 0; rb < 4; ++rb)
; #pragma unroll
;         for (int cb = 0; cb < 4; ++cb) *(LAS f32x4*)(P + (w * 64 + rb * 16 + fr) * 68 + cb * 16 + 4 * fq) = acc[rb][cb];
;     __syncthreads();
	v_mfma_f32_16x16x32_bf16 v[80:83], v[196:199], v[164:167], 0
	v_mfma_f32_16x16x32_bf16 v[84:87], v[200:203], v[164:167], 0
	v_mfma_f32_16x16x32_bf16 v[88:91], v[204:207], v[164:167], 0
	v_mfma_f32_16x16x32_bf16 v[92:95], v[208:211], v[164:167], 0
	v_mfma_f32_16x16x32_bf16 v[96:99], v[196:199], v[168:171], 0
	v_mfma_f32_16x16x32_bf16 v[100:103], v[200:203], v[168:171], 0
	v_mfma_f32_16x16x32_bf16 v[104:107], v[204:207], v[168:171], 0
	v_mfma_f32_16x16x32_bf16 v[108:111], v[208:211], v[168:171], 0
	v_mfma_f32_16x16x32_bf16 v[112:115], v[196:199], v[172:175], 0
	v_mfma_f32_16x16x32_bf16 v[116:119], v[200:203], v[172:175], 0
	v_mfma_f32_16x16x32_bf16 v[120:123], v[204:207], v[172:175], 0
	v_mfma_f32_16x16x32_bf16 v[124:127], v[208:211], v[172:175], 0
	v_mfma_f32_16x16x32_bf16 v[64:67], v[212:215], v[176:179], v[64:67]
	v_mfma_f32_16x16x32_bf16 v[68:71], v[216:219], v[176:179], v[68:71]
	v_mfma_f32_16x16x32_bf16 v[72:75], v[220:223], v[176:179], v[72:75]
	v_mfma_f32_16x16x32_bf16 v[76:79], v[224:227], v[176:179], v[76:79]
	v_mfma_f32_16x16x32_bf16 v[80:83], v[212:215], v[180:183], v[80:83]
	v_mfma_f32_16x16x32_bf16 v[84:87], v[216:219], v[180:183], v[84:87]
	v_mfma_f32_16x16x32_bf16 v[88:91], v[220:223], v[180:183], v[88:91]
	v_mfma_f32_16x16x32_bf16 v[92:95], v[224:227], v[180:183], v[92:95]
	v_mfma_f32_16x16x32_bf16 v[96:99], v[212:215], v[184:187], v[96:99]
	v_mfma_f32_16x16x32_bf16 v[100:103], v[216:219], v[184:187], v[100:103]
	v_mfma_f32_16x16x32_bf16 v[104:107], v[220:223], v[184:187], v[104:107]
	v_mfma_f32_16x16x32_bf16 v[108:111], v[224:227], v[184:187], v[108:111]
	v_mfma_f32_16x16x32_bf16 v[112:115], v[212:215], v[188:191], v[112:115]
	v_mfma_f32_16x16x32_bf16 v[116:119], v[216:219], v[188:191], v[116:119]
	v_mfma_f32_16x16x32_bf16 v[120:123], v[220:223], v[188:191], v[120:123]
	v_mfma_f32_16x16x32_bf16 v[124:127], v[224:227], v[188:191], v[124:127]
	s_waitcnt vmcnt(0)
	ds_read_b128 v[160:163], v27
	ds_read_b128 v[164:167], v27 offset:2048
	ds_read_b128 v[168:171], v27 offset:4096
	ds_read_b128 v[172:175], v27 offset:6144
	ds_read_b128 v[196:199], v27 offset:8192
	ds_read_b128 v[200:203], v27 offset:10240
	ds_read_b128 v[204:207], v27 offset:12288
	ds_read_b128 v[208:211], v27 offset:14336
	ds_read_b128 v[176:179], v28
	ds_read_b128 v[180:183], v28 offset:2048
	ds_read_b128 v[184:187], v28 offset:4096
	ds_read_b128 v[188:191], v28 offset:6144
	ds_read_b128 v[212:215], v28 offset:8192
	ds_read_b128 v[216:219], v28 offset:10240
	ds_read_b128 v[220:223], v28 offset:12288
	ds_read_b128 v[224:227], v28 offset:14336
	s_waitcnt lgkmcnt(0)
	v_mfma_f32_16x16x32_bf16 v[64:67], v[196:199], v[160:163], v[64:67]
	v_mfma_f32_16x16x32_bf16 v[68:71], v[200:203], v[160:163], v[68:71]
	v_mfma_f32_16x16x32_bf16 v[72:75], v[204:207], v[160:163], v[72:75]
	v_mfma_f32_16x16x32_bf16 v[76:79], v[208:211], v[160:163], v[76:79]
	v_mfma_f32_16x16x32_bf16 v[80:83], v[196:199], v[164:167], v[80:83]
	v_mfma_f32_16x16x32_bf16 v[84:87], v[200:203], v[164:167], v[84:87]
	v_mfma_f32_16x16x32_bf16 v[88:91], v[204:207], v[164:167], v[88:91]
	v_mfma_f32_16x16x32_bf16 v[92:95], v[208:211], v[164:167], v[92:95]
	v_mfma_f32_16x16x32_bf16 v[96:99], v[196:199], v[168:171], v[96:99]
	v_mfma_f32_16x16x32_bf16 v[100:103], v[200:203], v[168:171], v[100:103]
	v_mfma_f32_16x16x32_bf16 v[104:107], v[204:207], v[168:171], v[104:107]
	v_mfma_f32_16x16x32_bf16 v[108:111], v[208:211], v[168:171], v[108:111]
	v_mfma_f32_16x16x32_bf16 v[112:115], v[196:199], v[172:175], v[112:115]
	v_mfma_f32_16x16x32_bf16 v[116:119], v[200:203], v[172:175], v[116:119]
	v_mfma_f32_16x16x32_bf16 v[120:123], v[204:207], v[172:175], v[120:123]
	v_mfma_f32_16x16x32_bf16 v[124:127], v[208:211], v[172:175], v[124:127]
	v_mfma_f32_16x16x32_bf16 v[64:67], v[212:215], v[176:179], v[64:67]
	v_mfma_f32_16x16x32_bf16 v[68:71], v[216:219], v[176:179], v[68:71]
	v_mfma_f32_16x16x32_bf16 v[72:75], v[220:223], v[176:179], v[72:75]
	v_mfma_f32_16x16x32_bf16 v[76:79], v[224:227], v[176:179], v[76:79]
	v_mfma_f32_16x16x32_bf16 v[80:83], v[212:215], v[180:183], v[80:83]
	v_mfma_f32_16x16x32_bf16 v[84:87], v[216:219], v[180:183], v[84:87]
	v_mfma_f32_16x16x32_bf16 v[88:91], v[220:223], v[180:183], v[88:91]
	v_mfma_f32_16x16x32_bf16 v[92:95], v[224:227], v[180:183], v[92:95]
	v_mfma_f32_16x16x32_bf16 v[96:99], v[212:215], v[184:187], v[96:99]
	v_mfma_f32_16x16x32_bf16 v[100:103], v[216:219], v[184:187], v[100:103]
	v_mfma_f32_16x16x32_bf16 v[104:107], v[220:223], v[184:187], v[104:107]
	v_mfma_f32_16x16x32_bf16 v[108:111], v[224:227], v[184:187], v[108:111]
	v_mfma_f32_16x16x32_bf16 v[112:115], v[212:215], v[188:191], v[112:115]
	v_mfma_f32_16x16x32_bf16 v[116:119], v[216:219], v[188:191], v[116:119]
	v_mfma_f32_16x16x32_bf16 v[120:123], v[220:223], v[188:191], v[120:123]
	v_mfma_f32_16x16x32_bf16 v[124:127], v[224:227], v[188:191], v[124:127]
	s_and_b32 s7, s7, 0xfffffc0
	v_or_b32_e32 v2, s7, v29
	v_mul_lo_u32 v2, v2, s16
	v_add3_u32 v0, 0, v0, v2
	s_nop 7
	s_nop 7
	ds_write_b128 v0, v[64:67]
	ds_write_b128 v0, v[68:71] offset:64
	ds_write_b128 v0, v[72:75] offset:128
	ds_write_b128 v0, v[76:79] offset:192
	ds_write_b128 v0, v[80:83] offset:4352
	ds_write_b128 v0, v[84:87] offset:4416
	ds_write_b128 v0, v[88:91] offset:4480
	ds_write_b128 v0, v[92:95] offset:4544
	ds_write_b128 v0, v[96:99] offset:8704
	ds_write_b128 v0, v[100:103] offset:8768
	ds_write_b128 v0, v[104:107] offset:8832
	ds_write_b128 v0, v[108:111] offset:8896
	ds_write_b128 v0, v[112:115] offset:13056
	ds_write_b128 v0, v[116:119] offset:13120
	ds_write_b128 v0, v[120:123] offset:13184
	ds_write_b128 v0, v[124:127] offset:13248
	v_and_b32_e32 v34, 7, v7
	v_cmp_eq_u32_e32 vcc, 0, v34
	v_ashrrev_i32_e32 v12, 3, v7
	v_add_u32_e32 v2, s6, v12
	v_ashrrev_i32_e32 v3, 31, v2
	s_lshl_b32 s6, s0, 1
	v_mul_lo_u32 v7, v12, s16
	v_lshlrev_b64 v[8:9], 11, v[2:3]
	v_lshl_add_u64 v[8:9], s[34:35], 0, v[8:9]
	v_lshl_or_b32 v0, v34, 4, s6
	v_lshl_add_u64 v[24:25], v[8:9], 0, v[0:1]
	s_waitcnt lgkmcnt(0)
	s_barrier
; #define LAS __attribute__((address_space(3)))
; __device__ __forceinline__ void unpack8(const v4u w, float* f) { unpack2(w.x, f[0], f[1]); unpack2(w.y, f[2], f[3]); unpack2(w.z, f[4], f[5]); unpack2(w.w, f[6], f[7]); }
; __device__ __forceinline__ v4u pack8(const float* f) { v4u w; w.x = cvt_pk_bf16(f[0], f[1]); w.y = cvt_pk_bf16(f[2], f[3]); w.z = cvt_pk_bf16(f[4], f[5]); w.w = cvt_pk_bf16(f[6], f[7]); return w; }
;     __device__ __forceinline__ float elem8(int r, int c, f32x4 a0, f32x4 a1) const { float x[8] = {a0[0], a0[1], a0[2], a0[3], a1[0], a1[1], a1[2], a1[3]}; *(v4u*)(P + (size_t)r * D + c) = pack8(x); return 0.f; }
; template <class Elem>
; __device__ __forceinline__ void gemm_small64(LAS unsigned char* lds, const bf16* A, const bf16* Bt, int K, int r0, int c0, const Elem& E) {
;     ...
;     const int row = tid >> 3, c8 = (tid & 7) * 8;
;     f32x4 v0 = {0.f, 0.f, 0.f, 0.f}, v1 = {0.f, 0.f, 0.f, 0.f};
; #pragma unroll
;     for (int ww = 0; ww < 8; ++ww) { v0 += *(const LAS f32x4*)(P + (ww * 64 + row) * 68 + c8); v1 += *(const LAS f32x4*)(P + (ww * 64 + row) * 68 + c8 + 4); }
;     float ss = E.elem8(r0 + row, c0 + c8, v0, v1);
;     if (Elem::HAS_SS) { ss += __shfl_xor(ss, 1); ss += __shfl_xor(ss, 2); ss += __shfl_xor(ss, 4); if ((tid & 7) == 0) E.row_ss(r0 + row, c0 >> 6, ss); }
;     __syncthreads();
; }
;     __device__ __forceinline__ float elem8(int r, int c, f32x4 a0, f32x4 a1) const {
;         bf16* xp = XB + (size_t)r * D + c; float x[8]; unpack8(*(const v4u*)xp, x);
; #pragma unroll
;         for (int j = 0; j < 4; ++j) { x[j] += a0[j] * alpha; x[4 + j] += a1[j] * alpha; }
;         *(v4u*)xp = pack8(x);
;         float ss = 0.f;
; #pragma unroll
;         for (int j = 0; j < 8; ++j) ss += x[j] * x[j];
;         return ss;
;     }
	global_load_dwordx4 v[8:11], v[24:25], off
	v_lshlrev_b32_e32 v0, 5, v34
	v_add3_u32 v0, 0, v0, v7
	ds_read_b128 v[12:15], v0
	ds_read_b128 v[16:19], v0 offset:16
	ds_read_b128 v[20:23], v0 offset:17408
	v_add_u32_e32 v7, 0x11000, v0
	s_waitcnt lgkmcnt(2)
	v_pk_add_f32 v[26:27], v[14:15], 0 op_sel_hi:[1,0]
	v_pk_add_f32 v[28:29], v[12:13], 0 op_sel_hi:[1,0]
	ds_read_b128 v[12:15], v0 offset:17424
	s_waitcnt lgkmcnt(2)
	v_pk_add_f32 v[30:31], v[18:19], 0 op_sel_hi:[1,0]
	v_pk_add_f32 v[32:33], v[16:17], 0 op_sel_hi:[1,0]
	ds_read_b128 v[16:19], v0 offset:34816
	s_waitcnt lgkmcnt(2)
	v_pk_add_f32 v[26:27], v[26:27], v[22:23]
	s_waitcnt lgkmcnt(1)
	v_pk_add_f32 v[30:31], v[30:31], v[14:15]
	v_pk_add_f32 v[32:33], v[32:33], v[12:13]
	ds_read_b128 v[12:15], v0 offset:52224
	v_pk_add_f32 v[28:29], v[28:29], v[20:21]
	ds_read_b128 v[20:23], v0 offset:34832
	s_waitcnt lgkmcnt(2)
	v_pk_add_f32 v[26:27], v[26:27], v[18:19]
	v_pk_add_f32 v[28:29], v[28:29], v[16:17]
	ds_read_b128 v[16:19], v0 offset:52240
	s_waitcnt lgkmcnt(2)
	v_pk_add_f32 v[26:27], v[26:27], v[14:15]
	v_pk_add_f32 v[28:29], v[28:29], v[12:13]
	ds_read_b128 v[12:15], v7
	s_waitcnt lgkmcnt(2)
	v_pk_add_f32 v[22:23], v[30:31], v[22:23]
	v_pk_add_f32 v[20:21], v[32:33], v[20:21]
	v_add_u32_e32 v7, 0x11010, v0
	s_waitcnt lgkmcnt(1)
	v_pk_add_f32 v[22:23], v[22:23], v[18:19]
	v_pk_add_f32 v[20:21], v[20:21], v[16:17]
	ds_read_b128 v[16:19], v7
	v_add_u32_e32 v7, 0x15400, v0
	s_waitcnt lgkmcnt(1)
	v_pk_add_f32 v[26:27], v[26:27], v[14:15]
	v_pk_add_f32 v[28:29], v[28:29], v[12:13]
	ds_read_b128 v[12:15], v7
	v_add_u32_e32 v7, 0x15410, v0
	s_waitcnt lgkmcnt(1)
	v_pk_add_f32 v[22:23], v[22:23], v[18:19]
	v_pk_add_f32 v[20:21], v[20:21], v[16:17]
	ds_read_b128 v[16:19], v7
	v_add_u32_e32 v7, 0x19800, v0
	s_waitcnt lgkmcnt(1)
	v_pk_add_f32 v[26:27], v[26:27], v[14:15]
	v_pk_add_f32 v[28:29], v[28:29], v[12:13]
	ds_read_b128 v[12:15], v7
	v_add_u32_e32 v7, 0x19810, v0
	s_waitcnt lgkmcnt(1)
	v_pk_add_f32 v[30:31], v[22:23], v[18:19]
	v_pk_add_f32 v[32:33], v[20:21], v[16:17]
	ds_read_b128 v[16:19], v7
	v_add_u32_e32 v7, 0x1dc00, v0
	v_add_u32_e32 v0, 0x1dc10, v0
	s_waitcnt lgkmcnt(1)
	v_pk_add_f32 v[26:27], v[26:27], v[14:15]
	v_pk_add_f32 v[28:29], v[28:29], v[12:13]
	ds_read_b128 v[12:15], v7
	ds_read_b128 v[20:23], v0
	s_waitcnt lgkmcnt(2)
	v_pk_add_f32 v[16:17], v[32:33], v[16:17]
	v_pk_add_f32 v[18:19], v[30:31], v[18:19]
	s_waitcnt lgkmcnt(1)
	v_pk_add_f32 v[14:15], v[26:27], v[14:15]
	v_pk_add_f32 v[12:13], v[28:29], v[12:13]
	s_waitcnt lgkmcnt(0)
	v_pk_add_f32 v[16:17], v[16:17], v[20:21]
	v_pk_add_f32 v[18:19], v[18:19], v[22:23]
	s_waitcnt vmcnt(0)
	v_lshlrev_b32_e32 v20, 16, v8
	v_and_b32_e32 v21, 0xffff0000, v8
	v_lshlrev_b32_e32 v8, 16, v9
	v_and_b32_e32 v9, 0xffff0000, v9
	v_pk_add_f32 v[12:13], v[12:13], v[20:21]
	v_pk_add_f32 v[14:15], v[14:15], v[8:9]
	v_lshlrev_b32_e32 v8, 16, v11
	v_and_b32_e32 v9, 0xffff0000, v11
	v_pk_add_f32 v[18:19], v[18:19], v[8:9]
	v_pk_mul_f32 v[8:9], v[12:13], v[12:13]
	v_lshlrev_b32_e32 v20, 16, v10
	v_and_b32_e32 v21, 0xffff0000, v10
	v_pk_mul_f32 v[10:11], v[14:15], v[14:15]
	v_add_f32_e32 v0, v8, v9
	v_pk_add_f32 v[16:17], v[16:17], v[20:21]
	v_add_f32_e32 v0, v10, v0
	v_pk_mul_f32 v[20:21], v[16:17], v[16:17]
	v_add_f32_e32 v0, v11, v0
	v_add_f32_e32 v0, v20, v0
	v_pk_mul_f32 v[22:23], v[18:19], v[18:19]
	v_add_f32_e32 v0, v21, v0
	v_add_f32_e32 v0, v22, v0
	v_add_f32_e32 v0, v23, v0
	ds_bpermute_b32 v7, v4, v0
	v_cvt_pk_bf16_f32 v8, v12, v13
	v_cvt_pk_bf16_f32 v9, v14, v15
	v_cvt_pk_bf16_f32 v10, v16, v17
	v_cvt_pk_bf16_f32 v11, v18, v19
	s_waitcnt lgkmcnt(0)
	v_add_f32_e32 v0, v0, v7
	ds_bpermute_b32 v7, v5, v0
	global_store_dwordx4 v[24:25], v[8:11], off
	s_waitcnt lgkmcnt(0)
	v_add_f32_e32 v0, v0, v7
	ds_bpermute_b32 v7, v6, v0
	s_and_saveexec_b64 s[6:7], vcc
	s_cbranch_execz .LBB0_944
	v_lshlrev_b64 v[2:3], 6, v[2:3]
	v_lshl_add_u64 v[2:3], s[44:45], 0, v[2:3]
	s_lshr_b32 s0, s0, 4
	v_lshl_add_u64 v[2:3], v[2:3], 0, s[0:1]
	s_waitcnt lgkmcnt(0)
	v_add_f32_e32 v0, v0, v7
	global_store_dword v[2:3], v0, off
	s_branch .LBB0_944

; #define LAS __attribute__((address_space(3)))
; template <class Elem>
; __device__ __forceinline__ void gemm_small64(LAS unsigned char* lds, const bf16* A, const bf16* Bt, int K, int r0, int c0, const Elem& E) {
;     int tid_ = threadIdx.x; asm volatile("" : "+v"(tid_));
;     const int tid = tid_, lane = tid & 63, w = __builtin_amdgcn_readfirstlane(tid >> 6), fr = lane & 15, fq = lane >> 4;
;     const int kw = K >> 3, k0 = w * kw;
;     f32x4 acc[4][4];
; #pragma unroll
;     for (int i = 0; i < 4; ++i)
; #pragma unroll
;         for (int j = 0; j < 4; ++j) acc[i][j] = (f32x4){0.f, 0.f, 0.f, 0.f};
;     const bf16* ap = A + (size_t)(r0 + fr) * K + k0 + 8 * fq;
;     const bf16* bp = Bt + (size_t)(c0 + fr) * K + k0 + 8 * fq;
;     const size_t s16 = (size_t)16 * K;
; #pragma unroll 4
;     for (int ks = 0; ks < kw; ks += 32) {
;         bf16x8 a[4], b[4];
; #pragma unroll
;         for (int i = 0; i < 4; ++i) { a[i] = *(const bf16x8*)(ap + i * s16 + ks); b[i] = *(const bf16x8*)(bp + i * s16 + ks); }
; #pragma unroll
;         for (int rb = 0; rb < 4; ++rb)
; #pragma unroll
;             for (int cb = 0; cb < 4; ++cb) acc[rb][cb] = __builtin_amdgcn_mfma_f32_16x16x32_bf16(b[cb], a[rb], acc[rb][cb], 0, 0, 0);
;     }
.LBB0_1260:
	s_and_b32 s12, s3, 0xffffffc0
	v_mov_b32_e32 v95, v192
	s_addk_i32 s12, 0x4000
	s_and_b32 s11, s0, 0x3c0
	v_readfirstlane_b32 s13, v95
	v_and_b32_e32 v152, 15, v95
	s_lshl_b32 s14, s13, 1
	v_or_b32_e32 v2, s12, v152
	s_and_b32 s14, s14, 0xffffff80
	v_ashrrev_i32_e32 v3, 31, v2
	v_lshlrev_b64 v[2:3], 11, v[2:3]
	s_ashr_i32 s15, s14, 31
	v_or_b32_e32 v0, s11, v152
	v_lshl_add_u64 v[2:3], s[34:35], 0, v[2:3]
	s_lshl_b64 s[14:15], s[14:15], 1
	v_mov_b32_e32 v1, v93
	v_and_b32_e32 v92, 48, v95
	v_lshlrev_b32_e32 v0, 11, v0
	v_lshl_add_u64 v[2:3], v[2:3], 0, s[14:15]
	v_lshl_add_u64 v[0:1], s[6:7], 0, v[0:1]
	v_lshl_add_u64 v[116:117], v[2:3], 0, v[92:93]
	v_lshl_add_u64 v[0:1], v[0:1], 0, s[14:15]
	v_add_co_u32_e32 v128, vcc, s5, v116
	v_lshl_add_u64 v[118:119], v[0:1], 0, v[92:93]
	s_lshr_b32 s101, s13, 6
	v_mbcnt_lo_u32_b32 v50, -1, 0
	v_mbcnt_hi_u32_b32 v50, -1, v50
	v_lshrrev_b32_e32 v24, 3, v50
	v_and_b32_e32 v25, 7, v50
	v_lshrrev_b32_e32 v26, 1, v24
	v_xor_b32_e32 v27, v25, v26
	v_xor_b32_e32 v28, 4, v27
	v_mul_u32_u24_e32 v29, 0x800, v24
	v_lshl_add_u32 v30, v27, 4, v29
	v_lshl_add_u32 v31, v28, 4, v29
	v_mov_b32_e32 v33, 0x800
	v_mad_u32_u24 v32, v152, v33, v92
	v_sub_co_u32_e32 v34, vcc, v116, v32
	s_nop 1
	v_subbrev_co_u32_e32 v35, vcc, 0, v117, vcc
	v_sub_co_u32_e32 v40, vcc, v118, v32
	s_nop 1
	v_subbrev_co_u32_e32 v41, vcc, 0, v119, vcc
	v_mov_b32_e32 v16, v30
	v_add_u32_e32 v17, 0x4000, v31
	v_add_u32_e32 v18, 0x8000, v30
	v_add_u32_e32 v19, 0xc000, v31
	v_add_u32_e32 v20, 0x10000, v30
	v_add_u32_e32 v21, 0x14000, v31
	v_add_u32_e32 v22, 0x18000, v30
	v_add_u32_e32 v23, 0x1c000, v31
	v_readfirstlane_b32 s98, v34
	v_readfirstlane_b32 s99, v35
	v_readfirstlane_b32 s14, v40
	v_readfirstlane_b32 s15, v41
	s_nop 4
	s_mul_i32 s100, s101, 0x4400
	v_lshrrev_b32_e32 v43, 1, v152
	v_lshrrev_b32_e32 v46, 4, v92
	v_xor_b32_e32 v46, v46, v43
	v_lshlrev_b32_e32 v47, 7, v152
	v_lshl_add_u32 v47, v46, 4, v47
	v_add_u32_e32 v47, s100, v47
	v_xor_b32_e32 v48, 64, v47
	s_add_i32 m0, s100, 0x0
	s_nop 0
	global_load_lds_dwordx4 v16, s[98:99]
	s_add_i32 m0, s100, 0x400
	s_nop 0
	global_load_lds_dwordx4 v17, s[98:99]
	s_add_i32 m0, s100, 0x800
	s_nop 0
	global_load_lds_dwordx4 v18, s[98:99]
	s_add_i32 m0, s100, 0xc00
	s_nop 0
	global_load_lds_dwordx4 v19, s[98:99]
	s_add_i32 m0, s100, 0x1000
	s_nop 0
	global_load_lds_dwordx4 v20, s[98:99]
	s_add_i32 m0, s100, 0x1400
	s_nop 0
	global_load_lds_dwordx4 v21, s[98:99]
	s_add_i32 m0, s100, 0x1800
	s_nop 0
	global_load_lds_dwordx4 v22, s[98:99]
	s_add_i32 m0, s100, 0x1c00
	s_nop 0
	global_load_lds_dwordx4 v23, s[98:99]
	s_add_i32 m0, s100, 0x2000
	s_nop 0
	global_load_lds_dwordx4 v16, s[14:15]
	s_add_i32 m0, s100, 0x2400
	s_nop 0
	global_load_lds_dwordx4 v17, s[14:15]
	s_add_i32 m0, s100, 0x2800
	s_nop 0
	global_load_lds_dwordx4 v18, s[14:15]
	s_add_i32 m0, s100, 0x2c00
	s_nop 0
	global_load_lds_dwordx4 v19, s[14:15]
	s_add_i32 m0, s100, 0x3000
	s_nop 0
	global_load_lds_dwordx4 v20, s[14:15]
	s_add_i32 m0, s100, 0x3400
	s_nop 0
	global_load_lds_dwordx4 v21, s[14:15]
	s_add_i32 m0, s100, 0x3800
	s_nop 0
	global_load_lds_dwordx4 v22, s[14:15]
	s_add_i32 m0, s100, 0x3c00
	s_nop 0
	global_load_lds_dwordx4 v23, s[14:15]
	s_add_u32 s98, s98, 0x80
	s_addc_u32 s99, s99, 0
	s_add_u32 s14, s14, 0x80
	s_addc_u32 s15, s15, 0
	s_waitcnt vmcnt(0)
	ds_read_b128 v[164:167], v47
	ds_read_b128 v[168:171], v47 offset:2048
	ds_read_b128 v[172:175], v47 offset:4096
	ds_read_b128 v[176:179], v47 offset:6144
	ds_read_b128 v[136:139], v47 offset:8192
	ds_read_b128 v[140:143], v47 offset:10240
	ds_read_b128 v[144:147], v47 offset:12288
	ds_read_b128 v[148:151], v47 offset:14336
	ds_read_b128 v[180:183], v48
	ds_read_b128 v[184:187], v48 offset:2048
	ds_read_b128 v[188:191], v48 offset:4096
	ds_read_b128 v[132:135], v48 offset:6144
	ds_read_b128 v[0:3], v48 offset:8192
	ds_read_b128 v[4:7], v48 offset:10240
	ds_read_b128 v[8:11], v48 offset:12288
	ds_read_b128 v[12:15], v48 offset:14336
	s_waitcnt lgkmcnt(0)
	s_add_i32 m0, s100, 0x0
	s_nop 0
	global_load_lds_dwordx4 v16, s[98:99]
	s_add_i32 m0, s100, 0x400
	s_nop 0
	global_load_lds_dwordx4 v17, s[98:99]
	s_add_i32 m0, s100, 0x800
	s_nop 0
	global_load_lds_dwordx4 v18, s[98:99]
	s_add_i32 m0, s100, 0xc00
	s_nop 0
	global_load_lds_dwordx4 v19, s[98:99]
	s_add_i32 m0, s100, 0x1000
	s_nop 0
	global_load_lds_dwordx4 v20, s[98:99]
	s_add_i32 m0, s100, 0x1400
	s_nop 0
	global_load_lds_dwordx4 v21, s[98:99]
	s_add_i32 m0, s100, 0x1800
	s_nop 0
	global_load_lds_dwordx4 v22, s[98:99]
	s_add_i32 m0, s100, 0x1c00
	s_nop 0
	global_load_lds_dwordx4 v23, s[98:99]
	s_add_i32 m0, s100, 0x2000
	s_nop 0
	global_load_lds_dwordx4 v16, s[14:15]
	s_add_i32 m0, s100, 0x2400
	s_nop 0
	global_load_lds_dwordx4 v17, s[14:15]
	s_add_i32 m0, s100, 0x2800
	s_nop 0
	global_load_lds_dwordx4 v18, s[14:15]
	s_add_i32 m0, s100, 0x2c00
	s_nop 0
	global_load_lds_dwordx4 v19, s[14:15]
	s_add_i32 m0, s100, 0x3000
	s_nop 0
	global_load_lds_dwordx4 v20, s[14:15]
	s_add_i32 m0, s100, 0x3400
	s_nop 0
	global_load_lds_dwordx4 v21, s[14:15]
	s_add_i32 m0, s100, 0x3800
	s_nop 0
	global_load_lds_dwordx4 v22, s[14:15]
	s_add_i32 m0, s100, 0x3c00
	s_nop 0
	global_load_lds_dwordx4 v23, s[14:15]
	s_add_u32 s98, s98, 0x80
	s_addc_u32 s99, s99, 0
	s_add_u32 s14, s14, 0x80
	s_addc_u32 s15, s15, 0
	v_mfma_f32_16x16x32_bf16 v[196:199], v[136:139], v[164:167], 0
	v_mfma_f32_16x16x32_bf16 v[200:203], v[140:143], v[164:167], 0
	v_mfma_f32_16x16x32_bf16 v[204:207], v[144:147], v[164:167], 0
	v_mfma_f32_16x16x32_bf16 v[208:211], v[148:151], v[164:167], 0
	v_mfma_f32_16x16x32_bf16 v[212:215], v[136:139], v[168:171], 0
; #define LAS __attribute__((address_space(3)))
; template <class Elem>
; __device__ __forceinline__ void gemm_small64(LAS unsigned char* lds, const bf16* A, const bf16* Bt, int K, int r0, int c0, const Elem& E) {
;     ...
;     for (int ks = 0; ks < kw; ks += 32) {
;         bf16x8 a[4], b[4];
; #pragma unroll
;         for (int i = 0; i < 4; ++i) { a[i] = *(const bf16x8*)(ap + i * s16 + ks); b[i] = *(const bf16x8*)(bp + i * s16 + ks); }
; #pragma unroll
;         for (int rb = 0; rb < 4; ++rb)
; #pragma unroll
;             for (int cb = 0; cb < 4; ++cb) acc[rb][cb] = __builtin_amdgcn_mfma_f32_16x16x32_bf16(b[cb], a[rb], acc[rb][cb], 0, 0, 0);
;     }
;     LAS float* P = (LAS float*)lds;
; #pragma unroll
;     for (int rb = 0; rb < 4; ++rb)
; #pragma unroll
;         for (int cb = 0; cb < 4; ++cb) *(LAS f32x4*)(P + (w * 64 + rb * 16 + fr) * 68 + cb * 16 + 4 * fq) = acc[rb][cb];
;     __syncthreads();
	v_mfma_f32_16x16x32_bf16 v[216:219], v[140:143], v[168:171], 0
	v_mfma_f32_16x16x32_bf16 v[220:223], v[144:147], v[168:171], 0
	v_mfma_f32_16x16x32_bf16 v[224:227], v[148:151], v[168:171], 0
	v_mfma_f32_16x16x32_bf16 v[228:231], v[136:139], v[172:175], 0
	v_mfma_f32_16x16x32_bf16 v[232:235], v[140:143], v[172:175], 0
	v_mfma_f32_16x16x32_bf16 v[236:239], v[144:147], v[172:175], 0
	v_mfma_f32_16x16x32_bf16 v[240:243], v[148:151], v[172:175], 0
	v_mfma_f32_16x16x32_bf16 v[244:247], v[136:139], v[176:179], 0
	v_mfma_f32_16x16x32_bf16 v[248:251], v[140:143], v[176:179], 0
	v_mfma_f32_16x16x32_bf16 v[156:159], v[144:147], v[176:179], 0
	v_mfma_f32_16x16x32_bf16 v[160:163], v[148:151], v[176:179], 0
	v_mfma_f32_16x16x32_bf16 v[196:199], v[0:3], v[180:183], v[196:199]
	v_mfma_f32_16x16x32_bf16 v[200:203], v[4:7], v[180:183], v[200:203]
	v_mfma_f32_16x16x32_bf16 v[204:207], v[8:11], v[180:183], v[204:207]
	v_mfma_f32_16x16x32_bf16 v[208:211], v[12:15], v[180:183], v[208:211]
	v_mfma_f32_16x16x32_bf16 v[212:215], v[0:3], v[184:187], v[212:215]
	v_mfma_f32_16x16x32_bf16 v[216:219], v[4:7], v[184:187], v[216:219]
	v_mfma_f32_16x16x32_bf16 v[220:223], v[8:11], v[184:187], v[220:223]
	v_mfma_f32_16x16x32_bf16 v[224:227], v[12:15], v[184:187], v[224:227]
	v_mfma_f32_16x16x32_bf16 v[228:231], v[0:3], v[188:191], v[228:231]
	v_mfma_f32_16x16x32_bf16 v[232:235], v[4:7], v[188:191], v[232:235]
	v_mfma_f32_16x16x32_bf16 v[236:239], v[8:11], v[188:191], v[236:239]
	v_mfma_f32_16x16x32_bf16 v[240:243], v[12:15], v[188:191], v[240:243]
	v_mfma_f32_16x16x32_bf16 v[244:247], v[0:3], v[132:135], v[244:247]
	v_mfma_f32_16x16x32_bf16 v[248:251], v[4:7], v[132:135], v[248:251]
	v_mfma_f32_16x16x32_bf16 v[156:159], v[8:11], v[132:135], v[156:159]
	v_mfma_f32_16x16x32_bf16 v[160:163], v[12:15], v[132:135], v[160:163]
	s_waitcnt vmcnt(0)
	ds_read_b128 v[164:167], v47
	ds_read_b128 v[168:171], v47 offset:2048
	ds_read_b128 v[172:175], v47 offset:4096
	ds_read_b128 v[176:179], v47 offset:6144
	ds_read_b128 v[136:139], v47 offset:8192
	ds_read_b128 v[140:143], v47 offset:10240
	ds_read_b128 v[144:147], v47 offset:12288
	ds_read_b128 v[148:151], v47 offset:14336
	ds_read_b128 v[180:183], v48
	ds_read_b128 v[184:187], v48 offset:2048
	ds_read_b128 v[188:191], v48 offset:4096
	ds_read_b128 v[132:135], v48 offset:6144
	ds_read_b128 v[0:3], v48 offset:8192
	ds_read_b128 v[4:7], v48 offset:10240
	ds_read_b128 v[8:11], v48 offset:12288
	ds_read_b128 v[12:15], v48 offset:14336
	s_waitcnt lgkmcnt(0)
	v_mfma_f32_16x16x32_bf16 v[196:199], v[136:139], v[164:167], v[196:199]
	v_mfma_f32_16x16x32_bf16 v[200:203], v[140:143], v[164:167], v[200:203]
	v_mfma_f32_16x16x32_bf16 v[204:207], v[144:147], v[164:167], v[204:207]
	v_mfma_f32_16x16x32_bf16 v[208:211], v[148:151], v[164:167], v[208:211]
	v_mfma_f32_16x16x32_bf16 v[212:215], v[136:139], v[168:171], v[212:215]
	v_mfma_f32_16x16x32_bf16 v[216:219], v[140:143], v[168:171], v[216:219]
	v_mfma_f32_16x16x32_bf16 v[220:223], v[144:147], v[168:171], v[220:223]
	v_mfma_f32_16x16x32_bf16 v[224:227], v[148:151], v[168:171], v[224:227]
	v_mfma_f32_16x16x32_bf16 v[228:231], v[136:139], v[172:175], v[228:231]
	v_mfma_f32_16x16x32_bf16 v[232:235], v[140:143], v[172:175], v[232:235]
	v_mfma_f32_16x16x32_bf16 v[236:239], v[144:147], v[172:175], v[236:239]
	v_mfma_f32_16x16x32_bf16 v[240:243], v[148:151], v[172:175], v[240:243]
	v_mfma_f32_16x16x32_bf16 v[244:247], v[136:139], v[176:179], v[244:247]
	v_mfma_f32_16x16x32_bf16 v[248:251], v[140:143], v[176:179], v[248:251]
	v_mfma_f32_16x16x32_bf16 v[156:159], v[144:147], v[176:179], v[156:159]
	v_mfma_f32_16x16x32_bf16 v[160:163], v[148:151], v[176:179], v[160:163]
	v_mfma_f32_16x16x32_bf16 v[196:199], v[0:3], v[180:183], v[196:199]
	v_mfma_f32_16x16x32_bf16 v[200:203], v[4:7], v[180:183], v[200:203]
	v_mfma_f32_16x16x32_bf16 v[204:207], v[8:11], v[180:183], v[204:207]
	v_mfma_f32_16x16x32_bf16 v[208:211], v[12:15], v[180:183], v[208:211]
	v_mfma_f32_16x16x32_bf16 v[212:215], v[0:3], v[184:187], v[212:215]
	v_mfma_f32_16x16x32_bf16 v[216:219], v[4:7], v[184:187], v[216:219]
	v_mfma_f32_16x16x32_bf16 v[220:223], v[8:11], v[184:187], v[220:223]
	v_mfma_f32_16x16x32_bf16 v[224:227], v[12:15], v[184:187], v[224:227]
	v_mfma_f32_16x16x32_bf16 v[228:231], v[0:3], v[188:191], v[228:231]
	v_mfma_f32_16x16x32_bf16 v[232:235], v[4:7], v[188:191], v[232:235]
	v_mfma_f32_16x16x32_bf16 v[236:239], v[8:11], v[188:191], v[236:239]
	v_mfma_f32_16x16x32_bf16 v[240:243], v[12:15], v[188:191], v[240:243]
	v_mfma_f32_16x16x32_bf16 v[244:247], v[0:3], v[132:135], v[244:247]
	v_mfma_f32_16x16x32_bf16 v[248:251], v[4:7], v[132:135], v[248:251]
	v_mfma_f32_16x16x32_bf16 v[156:159], v[8:11], v[132:135], v[156:159]
	v_mfma_f32_16x16x32_bf16 v[160:163], v[12:15], v[132:135], v[160:163]
	s_and_b32 s13, s13, 0xfffffc0
	s_add_i32 s2, s2, s30
	s_add_i32 s0, s0, s1
	s_add_i32 s3, s3, s4
	s_cmpk_lt_i32 s2, 0x100
	v_ashrrev_i32_e32 v96, 3, v95
	v_lshlrev_b32_e32 v95, 3, v95
	v_add_u32_e32 v84, s12, v96
	v_ashrrev_i32_e32 v85, 31, v84
	v_and_b32_e32 v86, 56, v95
	v_or_b32_e32 v95, s13, v152
	v_mul_lo_u32 v95, v95, s10
	v_mul_lo_u32 v87, v96, s10
	v_lshlrev_b32_e32 v96, 2, v86
	v_add3_u32 v87, 0, v96, v87
	v_add_u32_e32 v98, 0x15410, v87
	v_add_u32_e32 v99, 0x19800, v87
	v_add_u32_e32 v100, 0x19810, v87
	v_add_u32_e32 v101, 0x1dc00, v87
	v_add_u32_e32 v102, 0x1dc10, v87
	v_lshlrev_b64 v[74:75], 10, v[84:85]
	v_lshlrev_b64 v[72:73], 6, v[84:85]
	v_or3_b32 v74, v86, s11, v74
	v_add3_u32 v84, 0, v92, v95
	v_add_u32_e32 v85, 0x11000, v87
	v_add_u32_e32 v92, 0x11010, v87
	v_add_u32_e32 v95, 0x15400, v87
	v_lshl_add_u64 v[96:97], v[74:75], 2, s[24:25]
	v_lshl_add_u64 v[52:53], s[44:45], 0, v[72:73]
	v_lshlrev_b64 v[44:45], 1, v[74:75]
	v_lshl_add_u64 v[36:37], s[34:35], 0, v[44:45]
	v_lshl_add_u64 v[38:39], s[46:47], 0, v[44:45]
	s_nop 7
	s_nop 7
	ds_write_b128 v84, v[196:199]
	ds_write_b128 v84, v[200:203] offset:64
	ds_write_b128 v84, v[204:207] offset:128
	ds_write_b128 v84, v[208:211] offset:192
	ds_write_b128 v84, v[212:215] offset:4352
	ds_write_b128 v84, v[216:219] offset:4416
	ds_write_b128 v84, v[220:223] offset:4480
	ds_write_b128 v84, v[224:227] offset:4544
	ds_write_b128 v84, v[228:231] offset:8704
	ds_write_b128 v84, v[232:235] offset:8768
	ds_write_b128 v84, v[236:239] offset:8832
	ds_write_b128 v84, v[240:243] offset:8896
	ds_write_b128 v84, v[244:247] offset:13056
	ds_write_b128 v84, v[248:251] offset:13120
	ds_write_b128 v84, v[156:159] offset:13184
	ds_write_b128 v84, v[160:163] offset:13248
	s_waitcnt lgkmcnt(0)
	s_barrier
; #define LAS __attribute__((address_space(3)))
; __device__ __forceinline__ void unpack8(const v4u w, float* f) { unpack2(w.x, f[0], f[1]); unpack2(w.y, f[2], f[3]); unpack2(w.z, f[4], f[5]); unpack2(w.w, f[6], f[7]); }
;     __device__ __forceinline__ float elem8(int r, int c, f32x4 a0, f32x4 a1) const { float x[8] = {a0[0], a0[1], a0[2], a0[3], a1[0], a1[1], a1[2], a1[3]}; *(v4u*)(P + (size_t)r * D + c) = pack8(x); return 0.f; }
; template <class Elem>
; __device__ __forceinline__ void gemm_small64(LAS unsigned char* lds, const bf16* A, const bf16* Bt, int K, int r0, int c0, const Elem& E) {
;     ...
;     const int row = tid >> 3, c8 = (tid & 7) * 8;
;     f32x4 v0 = {0.f, 0.f, 0.f, 0.f}, v1 = {0.f, 0.f, 0.f, 0.f};
; #pragma unroll
;     for (int ww = 0; ww < 8; ++ww) { v0 += *(const LAS f32x4*)(P + (ww * 64 + row) * 68 + c8); v1 += *(const LAS f32x4*)(P + (ww * 64 + row) * 68 + c8 + 4); }
;     float ss = E.elem8(r0 + row, c0 + c8, v0, v1);
;     if (Elem::HAS_SS) { ss += __shfl_xor(ss, 1); ss += __shfl_xor(ss, 2); ss += __shfl_xor(ss, 4); if ((tid & 7) == 0) E.row_ss(r0 + row, c0 >> 6, ss); }
;     __device__ __forceinline__ float elem8(int r, int c, f32x4 a0, f32x4 a1) const {
;         const float rs = pg8::row_rs(SS, r); const size_t off = (size_t)r * D + c;
;         float x[8], p[8]; unpack8(*(const v4u*)(XB + off), x); unpack8(*(const v4u*)(P + off), p); f32x4 o0, o1;
; #pragma unroll
;         for (int j = 0; j < 4; ++j) { o0[j] = x[j] + __builtin_amdgcn_rcpf(1.0f + __expf(-a0[j] * rs)) * p[j]; o1[j] = x[4 + j] + __builtin_amdgcn_rcpf(1.0f + __expf(-a1[j] * rs)) * p[4 + j]; }
;         *(f32x4*)(Y + off) = o0; *(f32x4*)(Y + off + 4) = o1; return 0.f;
;     }
	global_load_dwordx4 v[0:3], v[52:53], off
	global_load_dwordx4 v[4:7], v[52:53], off offset:16
	global_load_dwordx4 v[8:11], v[52:53], off offset:32
	global_load_dwordx4 v[12:15], v[52:53], off offset:48
	global_load_dwordx4 v[16:19], v[36:37], off
	global_load_dwordx4 v[20:23], v[38:39], off
	ds_read_b128 v[24:27], v87
	ds_read_b128 v[28:31], v87 offset:16
	ds_read_b128 v[32:35], v87 offset:17408
	ds_read_b128 v[36:39], v87 offset:17424
	ds_read_b128 v[40:43], v87 offset:34816
	ds_read_b128 v[44:47], v87 offset:34832
	ds_read_b128 v[48:51], v87 offset:52224
	ds_read_b128 v[52:55], v87 offset:52240
	ds_read_b128 v[56:59], v85
	ds_read_b128 v[60:63], v92
	ds_read_b128 v[64:67], v95
	ds_read_b128 v[68:71], v98
	ds_read_b128 v[72:75], v99
	ds_read_b128 v[76:79], v100
	ds_read_b128 v[80:83], v101
	ds_read_b128 v[84:87], v102
	s_waitcnt lgkmcnt(14)
	v_pk_add_f32 v[26:27], v[26:27], 0 op_sel_hi:[1,0]
	v_pk_add_f32 v[24:25], v[24:25], 0 op_sel_hi:[1,0]
	v_pk_add_f32 v[28:29], v[28:29], 0 op_sel_hi:[1,0]
	v_pk_add_f32 v[30:31], v[30:31], 0 op_sel_hi:[1,0]
	s_waitcnt lgkmcnt(13)
	v_pk_add_f32 v[26:27], v[26:27], v[34:35]
	v_pk_add_f32 v[24:25], v[24:25], v[32:33]
	s_waitcnt lgkmcnt(12)
	v_pk_add_f32 v[28:29], v[28:29], v[36:37]
	v_pk_add_f32 v[30:31], v[30:31], v[38:39]
	s_waitcnt lgkmcnt(11)
	v_pk_add_f32 v[26:27], v[26:27], v[42:43]
	v_pk_add_f32 v[24:25], v[24:25], v[40:41]
	s_waitcnt lgkmcnt(10)
	v_pk_add_f32 v[28:29], v[28:29], v[44:45]
	v_pk_add_f32 v[30:31], v[30:31], v[46:47]
	s_waitcnt lgkmcnt(9)
	v_pk_add_f32 v[26:27], v[26:27], v[50:51]
	v_pk_add_f32 v[24:25], v[24:25], v[48:49]
	s_waitcnt lgkmcnt(8)
	v_pk_add_f32 v[28:29], v[28:29], v[52:53]
	v_pk_add_f32 v[30:31], v[30:31], v[54:55]
	s_waitcnt lgkmcnt(7)
	v_pk_add_f32 v[26:27], v[26:27], v[58:59]
	v_pk_add_f32 v[24:25], v[24:25], v[56:57]
	s_waitcnt lgkmcnt(6)
	v_pk_add_f32 v[28:29], v[28:29], v[60:61]
	v_pk_add_f32 v[30:31], v[30:31], v[62:63]
	s_waitcnt lgkmcnt(5)
	v_pk_add_f32 v[26:27], v[26:27], v[66:67]
	v_pk_add_f32 v[24:25], v[24:25], v[64:65]
	s_waitcnt lgkmcnt(4)
	v_pk_add_f32 v[28:29], v[28:29], v[68:69]
	v_pk_add_f32 v[30:31], v[30:31], v[70:71]
	s_waitcnt lgkmcnt(3)
	v_pk_add_f32 v[26:27], v[26:27], v[74:75]
	v_pk_add_f32 v[24:25], v[24:25], v[72:73]
	s_waitcnt lgkmcnt(2)
	v_pk_add_f32 v[28:29], v[28:29], v[76:77]
	v_pk_add_f32 v[30:31], v[30:31], v[78:79]
	s_waitcnt lgkmcnt(1)
	v_pk_add_f32 v[26:27], v[26:27], v[82:83]
	v_pk_add_f32 v[24:25], v[24:25], v[80:81]
	s_waitcnt lgkmcnt(0)
	v_pk_add_f32 v[28:29], v[28:29], v[84:85]
	v_pk_add_f32 v[30:31], v[30:31], v[86:87]
	s_waitcnt vmcnt(4)
	v_pk_add_f32 v[2:3], v[2:3], v[6:7]
	v_pk_add_f32 v[0:1], v[0:1], v[4:5]
	s_waitcnt vmcnt(2)
	v_pk_add_f32 v[4:5], v[10:11], v[14:15]
	v_pk_add_f32 v[6:7], v[8:9], v[12:13]
	v_pk_add_f32 v[2:3], v[2:3], v[4:5]
	v_pk_add_f32 v[0:1], v[0:1], v[6:7]
	s_waitcnt vmcnt(1)
	v_lshlrev_b32_e32 v8, 16, v16
	v_pk_mov_b32 v[4:5], v[0:1], v[2:3] op_sel:[1,0]
	v_mov_b32_e32 v1, v3
	v_pk_add_f32 v[0:1], v[4:5], v[0:1]
	v_and_b32_e32 v9, 0xffff0000, v16
	v_add_f32_e32 v0, v0, v1
	v_fmamk_f32 v0, v0, 0x3a800000, v94
	v_rsq_f32_e32 v0, v0
	s_waitcnt vmcnt(0)
	v_lshlrev_b32_e32 v10, 16, v20
	v_and_b32_e32 v11, 0xffff0000, v20
	v_lshlrev_b32_e32 v12, 16, v18
	v_mul_f32_e64 v1, v0, -v24
	v_mul_f32_e64 v2, v0, -v28
	v_mul_f32_e64 v3, v0, -v25
	v_mul_f32_e64 v4, v0, -v29
	v_mul_f32_e64 v5, v0, -v26
	v_mul_f32_e64 v7, v0, -v27
	v_mul_f32_e64 v6, v0, -v30
	v_mul_f32_e64 v0, v0, -v31
	v_mul_f32_e32 v1, 0x3fb8aa3b, v1
	v_mul_f32_e32 v2, 0x3fb8aa3b, v2
	v_mul_f32_e32 v3, 0x3fb8aa3b, v3
	v_mul_f32_e32 v4, 0x3fb8aa3b, v4
	v_mul_f32_e32 v5, 0x3fb8aa3b, v5
	v_mul_f32_e32 v7, 0x3fb8aa3b, v7
	v_mul_f32_e32 v6, 0x3fb8aa3b, v6
	v_mul_f32_e32 v0, 0x3fb8aa3b, v0
	v_exp_f32_e32 v1, v1
	v_exp_f32_e32 v2, v2
	v_exp_f32_e32 v3, v3
	v_exp_f32_e32 v4, v4
	v_exp_f32_e32 v5, v5
	v_exp_f32_e32 v7, v7
	v_exp_f32_e32 v6, v6
	v_exp_f32_e32 v0, v0
	v_add_f32_e32 v1, 1.0, v1
	v_add_f32_e32 v2, 1.0, v2
	v_add_f32_e32 v3, 1.0, v3
	v_add_f32_e32 v4, 1.0, v4
	v_add_f32_e32 v5, 1.0, v5
	v_add_f32_e32 v7, 1.0, v7
	v_add_f32_e32 v24, 1.0, v6
	v_add_f32_e32 v25, 1.0, v0
	v_rcp_f32_e32 v0, v1
	v_rcp_f32_e32 v2, v2
	v_rcp_f32_e32 v1, v3
	v_rcp_f32_e32 v3, v4
	v_rcp_f32_e32 v6, v5
	v_rcp_f32_e32 v7, v7
	v_rcp_f32_e32 v24, v24
	v_rcp_f32_e32 v25, v25
	v_and_b32_e32 v13, 0xffff0000, v18
	v_lshlrev_b32_e32 v14, 16, v22
	v_and_b32_e32 v15, 0xffff0000, v22
	v_lshlrev_b32_e32 v16, 16, v17
	v_and_b32_e32 v17, 0xffff0000, v17
	v_lshlrev_b32_e32 v20, 16, v21
	v_and_b32_e32 v21, 0xffff0000, v21
	v_lshlrev_b32_e32 v18, 16, v19
	v_and_b32_e32 v19, 0xffff0000, v19
	v_lshlrev_b32_e32 v22, 16, v23
	v_and_b32_e32 v23, 0xffff0000, v23
	v_pk_fma_f32 v[0:1], v[0:1], v[10:11], v[8:9]
	v_pk_fma_f32 v[4:5], v[2:3], v[14:15], v[12:13]
	v_pk_fma_f32 v[2:3], v[6:7], v[20:21], v[16:17]
	v_pk_fma_f32 v[6:7], v[24:25], v[22:23], v[18:19]
	global_store_dwordx4 v[96:97], v[0:3], off
	global_store_dwordx4 v[96:97], v[4:7], off offset:16
	s_barrier
	s_cbranch_scc1 .LBB0_1260
